# idx compaction bisection loops: per-lane v_addc counting + DPP wave reduce instead of 16 serial vcc/s_bcnt1 (8 loops); plus c2
# speedup vs baseline: 1.0420x; 1.0032x over previous
;     unsigned mx = 0u, mn = 0xFFFFFFFFu;
; #pragma unroll
;     for (int j = 0; j < NE; ++j) { mx = max(mx, e[j]); mn = min(mn, e[j] ? e[j] : 0xFFFFFFFFu); }
; #pragma unroll
;     for (int o = 1; o < 64; o <<= 1) { mx = max(mx, (unsigned)__shfl_xor((int)mx, o)); mn = min(mn, (unsigned)__shfl_xor((int)mn, o)); }
;     const unsigned dif = mx ^ mn;
;     const int hb = dif ? 31 - __clz((int)dif) : -1;
;     unsigned tau = hb >= 31 ? 0u : (hb < 0 ? mx : (mx & ~((2u << hb) - 1u)));
;     ...
; #pragma unroll
;         for (int j = 0; j < NE; ++j) c += __popcll(__ballot(e[j] >= cand));
;         if (c >= kth) tau = cand; }
.LBB0_1265:
	v_lshl_or_b32 v50, 1, v49, v48
	v_mov_b32_e32 v60, 0
	v_cmp_ge_u32_e32 vcc, v34, v50
	v_cmp_ge_u32_e64 s[98:99], v35, v50
	v_cmp_ge_u32_e64 s[100:101], v32, v50
	v_addc_co_u32_e32 v60, vcc, 0, v60, vcc
	v_addc_co_u32_e64 v60, s[98:99], 0, v60, s[98:99]
	v_addc_co_u32_e64 v60, s[100:101], 0, v60, s[100:101]
	v_cmp_ge_u32_e32 vcc, v33, v50
	v_cmp_ge_u32_e64 s[98:99], v47, v50
	v_cmp_ge_u32_e64 s[100:101], v45, v50
	v_addc_co_u32_e32 v60, vcc, 0, v60, vcc
	v_addc_co_u32_e64 v60, s[98:99], 0, v60, s[98:99]
	v_addc_co_u32_e64 v60, s[100:101], 0, v60, s[100:101]
	v_cmp_ge_u32_e32 vcc, v46, v50
	v_cmp_ge_u32_e64 s[98:99], v43, v50
	v_cmp_ge_u32_e64 s[100:101], v44, v50
	v_addc_co_u32_e32 v60, vcc, 0, v60, vcc
	v_addc_co_u32_e64 v60, s[98:99], 0, v60, s[98:99]
	v_addc_co_u32_e64 v60, s[100:101], 0, v60, s[100:101]
	v_cmp_ge_u32_e32 vcc, v41, v50
	v_cmp_ge_u32_e64 s[98:99], v42, v50
	v_cmp_ge_u32_e64 s[100:101], v39, v50
	v_addc_co_u32_e32 v60, vcc, 0, v60, vcc
	v_addc_co_u32_e64 v60, s[98:99], 0, v60, s[98:99]
	v_addc_co_u32_e64 v60, s[100:101], 0, v60, s[100:101]
	v_cmp_ge_u32_e32 vcc, v40, v50
	v_cmp_ge_u32_e64 s[98:99], v37, v50
	v_cmp_ge_u32_e64 s[100:101], v38, v50
	v_addc_co_u32_e32 v60, vcc, 0, v60, vcc
	v_addc_co_u32_e64 v60, s[98:99], 0, v60, s[98:99]
	v_addc_co_u32_e64 v60, s[100:101], 0, v60, s[100:101]
	v_cmp_ge_u32_e32 vcc, v36, v50
	s_nop 1
	v_addc_co_u32_e32 v60, vcc, 0, v60, vcc
	s_nop 1
	v_add_u32_dpp v60, v60, v60 row_shr:1 row_mask:0xf bank_mask:0xf bound_ctrl:0
	s_nop 1
	v_add_u32_dpp v60, v60, v60 row_shr:2 row_mask:0xf bank_mask:0xf bound_ctrl:0
	s_nop 1
	v_add_u32_dpp v60, v60, v60 row_shr:4 row_mask:0xf bank_mask:0xf bound_ctrl:0
	s_nop 1
	v_add_u32_dpp v60, v60, v60 row_shr:8 row_mask:0xf bank_mask:0xf bound_ctrl:0
	s_nop 1
	v_add_u32_dpp v60, v60, v60 row_bcast:15 row_mask:0xa bank_mask:0xf
	s_nop 1
	v_add_u32_dpp v60, v60, v60 row_bcast:31 row_mask:0xc bank_mask:0xf
	s_nop 1
	v_readlane_b32 s11, v60, 63
	s_cmpk_gt_u32 s11, 0xff
	s_cselect_b64 vcc, -1, 0
	v_cndmask_b32_e32 v48, v48, v50, vcc
	v_add_u32_e32 v50, -1, v49
	v_cmp_gt_u32_e32 vcc, 15, v49
	s_or_b64 s[2:3], vcc, s[2:3]
	v_mov_b32_e32 v49, v50
	s_andn2_b64 exec, exec, s[2:3]
	s_cbranch_execnz .LBB0_1265
	s_or_b64 exec, exec, s[2:3]

;     unsigned mx = 0u, mn = 0xFFFFFFFFu;
; #pragma unroll
;     for (int j = 0; j < NE; ++j) { mx = max(mx, e[j]); mn = min(mn, e[j] ? e[j] : 0xFFFFFFFFu); }
; #pragma unroll
;     for (int o = 1; o < 64; o <<= 1) { mx = max(mx, (unsigned)__shfl_xor((int)mx, o)); mn = min(mn, (unsigned)__shfl_xor((int)mn, o)); }
;     const unsigned dif = mx ^ mn;
;     const int hb = dif ? 31 - __clz((int)dif) : -1;
;     unsigned tau = hb >= 31 ? 0u : (hb < 0 ? mx : (mx & ~((2u << hb) - 1u)));
;     ...
; #pragma unroll
;         for (int j = 0; j < NE; ++j) c += __popcll(__ballot(e[j] >= cand));
;         if (c >= kth) tau = cand; }
.LBB0_1524:
	v_lshl_or_b32 v18, 1, v17, v16
	v_mov_b32_e32 v60, 0
	v_cmp_ge_u32_e32 vcc, v2, v18
	v_cmp_ge_u32_e64 s[98:99], v3, v18
	v_cmp_ge_u32_e64 s[100:101], v0, v18
	v_addc_co_u32_e32 v60, vcc, 0, v60, vcc
	v_addc_co_u32_e64 v60, s[98:99], 0, v60, s[98:99]
	v_addc_co_u32_e64 v60, s[100:101], 0, v60, s[100:101]
	v_cmp_ge_u32_e32 vcc, v1, v18
	v_cmp_ge_u32_e64 s[98:99], v15, v18
	v_cmp_ge_u32_e64 s[100:101], v14, v18
	v_addc_co_u32_e32 v60, vcc, 0, v60, vcc
	v_addc_co_u32_e64 v60, s[98:99], 0, v60, s[98:99]
	v_addc_co_u32_e64 v60, s[100:101], 0, v60, s[100:101]
	v_cmp_ge_u32_e32 vcc, v13, v18
	v_cmp_ge_u32_e64 s[98:99], v12, v18
	v_cmp_ge_u32_e64 s[100:101], v11, v18
	v_addc_co_u32_e32 v60, vcc, 0, v60, vcc
	v_addc_co_u32_e64 v60, s[98:99], 0, v60, s[98:99]
	v_addc_co_u32_e64 v60, s[100:101], 0, v60, s[100:101]
	v_cmp_ge_u32_e32 vcc, v10, v18
	v_cmp_ge_u32_e64 s[98:99], v9, v18
	v_cmp_ge_u32_e64 s[100:101], v8, v18
	v_addc_co_u32_e32 v60, vcc, 0, v60, vcc
	v_addc_co_u32_e64 v60, s[98:99], 0, v60, s[98:99]
	v_addc_co_u32_e64 v60, s[100:101], 0, v60, s[100:101]
	v_cmp_ge_u32_e32 vcc, v7, v18
	v_cmp_ge_u32_e64 s[98:99], v6, v18
	v_cmp_ge_u32_e64 s[100:101], v5, v18
	v_addc_co_u32_e32 v60, vcc, 0, v60, vcc
	v_addc_co_u32_e64 v60, s[98:99], 0, v60, s[98:99]
	v_addc_co_u32_e64 v60, s[100:101], 0, v60, s[100:101]
	v_cmp_ge_u32_e32 vcc, v4, v18
	s_nop 1
	v_addc_co_u32_e32 v60, vcc, 0, v60, vcc
	s_nop 1
	v_add_u32_dpp v60, v60, v60 row_shr:1 row_mask:0xf bank_mask:0xf bound_ctrl:0
	s_nop 1
	v_add_u32_dpp v60, v60, v60 row_shr:2 row_mask:0xf bank_mask:0xf bound_ctrl:0
	s_nop 1
	v_add_u32_dpp v60, v60, v60 row_shr:4 row_mask:0xf bank_mask:0xf bound_ctrl:0
	s_nop 1
	v_add_u32_dpp v60, v60, v60 row_shr:8 row_mask:0xf bank_mask:0xf bound_ctrl:0
	s_nop 1
	v_add_u32_dpp v60, v60, v60 row_bcast:15 row_mask:0xa bank_mask:0xf
	s_nop 1
	v_add_u32_dpp v60, v60, v60 row_bcast:31 row_mask:0xc bank_mask:0xf
	s_nop 1
	v_readlane_b32 s8, v60, 63
	s_cmpk_gt_u32 s8, 0xff
	s_cselect_b64 vcc, -1, 0
	v_cndmask_b32_e32 v16, v16, v18, vcc
	v_add_u32_e32 v18, -1, v17
	v_cmp_gt_u32_e32 vcc, 15, v17
	s_or_b64 s[2:3], vcc, s[2:3]
	v_mov_b32_e32 v17, v18
	s_andn2_b64 exec, exec, s[2:3]
	s_cbranch_execnz .LBB0_1524
	s_or_b64 exec, exec, s[2:3]

;     unsigned mx = 0u, mn = 0xFFFFFFFFu;
; #pragma unroll
;     for (int j = 0; j < NE; ++j) { mx = max(mx, e[j]); mn = min(mn, e[j] ? e[j] : 0xFFFFFFFFu); }
; #pragma unroll
;     for (int o = 1; o < 64; o <<= 1) { mx = max(mx, (unsigned)__shfl_xor((int)mx, o)); mn = min(mn, (unsigned)__shfl_xor((int)mn, o)); }
;     const unsigned dif = mx ^ mn;
;     const int hb = dif ? 31 - __clz((int)dif) : -1;
;     unsigned tau = hb >= 31 ? 0u : (hb < 0 ? mx : (mx & ~((2u << hb) - 1u)));
;     ...
; #pragma unroll
;         for (int j = 0; j < NE; ++j) c += __popcll(__ballot(e[j] >= cand));
;         if (c >= kth) tau = cand; }
.LBB0_1601:
	v_lshl_or_b32 v20, 1, v19, v18
	v_mov_b32_e32 v60, 0
	v_cmp_ge_u32_e32 vcc, v4, v20
	v_cmp_ge_u32_e64 s[98:99], v5, v20
	v_cmp_ge_u32_e64 s[100:101], v2, v20
	v_addc_co_u32_e32 v60, vcc, 0, v60, vcc
	v_addc_co_u32_e64 v60, s[98:99], 0, v60, s[98:99]
	v_addc_co_u32_e64 v60, s[100:101], 0, v60, s[100:101]
	v_cmp_ge_u32_e32 vcc, v3, v20
	v_cmp_ge_u32_e64 s[98:99], v17, v20
	v_cmp_ge_u32_e64 s[100:101], v16, v20
	v_addc_co_u32_e32 v60, vcc, 0, v60, vcc
	v_addc_co_u32_e64 v60, s[98:99], 0, v60, s[98:99]
	v_addc_co_u32_e64 v60, s[100:101], 0, v60, s[100:101]
	v_cmp_ge_u32_e32 vcc, v15, v20
	v_cmp_ge_u32_e64 s[98:99], v14, v20
	v_cmp_ge_u32_e64 s[100:101], v13, v20
	v_addc_co_u32_e32 v60, vcc, 0, v60, vcc
	v_addc_co_u32_e64 v60, s[98:99], 0, v60, s[98:99]
	v_addc_co_u32_e64 v60, s[100:101], 0, v60, s[100:101]
	v_cmp_ge_u32_e32 vcc, v12, v20
	v_cmp_ge_u32_e64 s[98:99], v11, v20
	v_cmp_ge_u32_e64 s[100:101], v10, v20
	v_addc_co_u32_e32 v60, vcc, 0, v60, vcc
	v_addc_co_u32_e64 v60, s[98:99], 0, v60, s[98:99]
	v_addc_co_u32_e64 v60, s[100:101], 0, v60, s[100:101]
	v_cmp_ge_u32_e32 vcc, v9, v20
	v_cmp_ge_u32_e64 s[98:99], v8, v20
	v_cmp_ge_u32_e64 s[100:101], v7, v20
	v_addc_co_u32_e32 v60, vcc, 0, v60, vcc
	v_addc_co_u32_e64 v60, s[98:99], 0, v60, s[98:99]
	v_addc_co_u32_e64 v60, s[100:101], 0, v60, s[100:101]
	v_cmp_ge_u32_e32 vcc, v6, v20
	s_nop 1
	v_addc_co_u32_e32 v60, vcc, 0, v60, vcc
	s_nop 1
	v_add_u32_dpp v60, v60, v60 row_shr:1 row_mask:0xf bank_mask:0xf bound_ctrl:0
	s_nop 1
	v_add_u32_dpp v60, v60, v60 row_shr:2 row_mask:0xf bank_mask:0xf bound_ctrl:0
	s_nop 1
	v_add_u32_dpp v60, v60, v60 row_shr:4 row_mask:0xf bank_mask:0xf bound_ctrl:0
	s_nop 1
	v_add_u32_dpp v60, v60, v60 row_shr:8 row_mask:0xf bank_mask:0xf bound_ctrl:0
	s_nop 1
	v_add_u32_dpp v60, v60, v60 row_bcast:15 row_mask:0xa bank_mask:0xf
	s_nop 1
	v_add_u32_dpp v60, v60, v60 row_bcast:31 row_mask:0xc bank_mask:0xf
	s_nop 1
	v_readlane_b32 s8, v60, 63
	s_cmpk_gt_u32 s8, 0xff
	s_cselect_b64 vcc, -1, 0
	v_cndmask_b32_e32 v18, v18, v20, vcc
	v_add_u32_e32 v20, -1, v19
	v_cmp_gt_u32_e32 vcc, 15, v19
	s_or_b64 s[2:3], vcc, s[2:3]
	v_mov_b32_e32 v19, v20
	s_andn2_b64 exec, exec, s[2:3]
	s_cbranch_execnz .LBB0_1601
	s_or_b64 exec, exec, s[2:3]
